# speedup vs baseline: 1.0075x; 1.0075x over previous
.Lbk64_418:
	s_waitcnt vmcnt(0)
	s_barrier
	ds_read_b128 v[192:195], v227
	ds_read_b128 v[196:199], v228
	ds_read_b128 v[200:203], v227 offset:2048
	ds_read_b128 v[204:207], v228 offset:2048
	ds_read_b128 v[208:211], v227 offset:4096
	ds_read_b128 v[212:215], v228 offset:4096
	ds_read_b128 v[216:219], v227 offset:6144
	ds_read_b128 v[220:223], v228 offset:6144
	s_add_u32 s4, s4, 0x80
	s_addc_u32 s5, s5, 0
	s_add_u32 s22, s22, 0x80
	s_addc_u32 s23, s23, 0
	s_waitcnt lgkmcnt(0)
	s_barrier
	ds_read_b128 v[154:157], v229 offset:0
	ds_read_b128 v[158:161], v230 offset:0
	ds_read_b128 v[162:165], v229 offset:2048
	ds_read_b128 v[166:169], v230 offset:2048
	s_waitcnt lgkmcnt(2)
	v_mfma_f32_16x16x32_bf16 v[126:129], v[192:195], v[154:157], v[126:129]
	v_mfma_f32_16x16x32_bf16 v[114:117], v[200:203], v[154:157], v[114:117]
	v_mfma_f32_16x16x32_bf16 v[94:97], v[208:211], v[154:157], v[94:97]
	v_mfma_f32_16x16x32_bf16 v[62:65], v[216:219], v[154:157], v[62:65]
	v_readfirstlane_b32 s32, v142
	s_lshl_b32 m0, s32, 3
	v_add_u32_e32 v226, 0, v224
	v_max_i32_e32 v226, 0, v226
	v_min_i32_e32 v226, 0xffff, v226
	v_lshl_add_u32 v226, v226, 11, v231
	global_load_lds_dwordx4 v226, s[4:5]
	v_mfma_f32_16x16x32_bf16 v[126:129], v[196:199], v[158:161], v[126:129]
	v_mfma_f32_16x16x32_bf16 v[114:117], v[204:207], v[158:161], v[114:117]
	v_mfma_f32_16x16x32_bf16 v[94:97], v[212:215], v[158:161], v[94:97]
	v_mfma_f32_16x16x32_bf16 v[62:65], v[220:223], v[158:161], v[62:65]
	s_add_u32 m0, m0, 0x400
	v_add_u32_e32 v226, 8, v224
	v_max_i32_e32 v226, 0, v226
	v_min_i32_e32 v226, 0xffff, v226
	v_lshl_add_u32 v226, v226, 11, v231
	global_load_lds_dwordx4 v226, s[4:5]
	ds_read_b128 v[154:157], v229 offset:4096
	ds_read_b128 v[158:161], v230 offset:4096
	s_waitcnt lgkmcnt(2)
	v_mfma_f32_16x16x32_bf16 v[122:125], v[192:195], v[162:165], v[122:125]
	v_mfma_f32_16x16x32_bf16 v[106:109], v[200:203], v[162:165], v[106:109]
	v_mfma_f32_16x16x32_bf16 v[78:81], v[208:211], v[162:165], v[78:81]
	v_mfma_f32_16x16x32_bf16 v[46:49], v[216:219], v[162:165], v[46:49]
	s_add_u32 m0, m0, 0x400
	v_add_u32_e32 v226, 16, v224
	v_max_i32_e32 v226, 0, v226
	v_min_i32_e32 v226, 0xffff, v226
	v_lshl_add_u32 v226, v226, 11, v231
	global_load_lds_dwordx4 v226, s[4:5]
	v_mfma_f32_16x16x32_bf16 v[122:125], v[196:199], v[166:169], v[122:125]
	v_mfma_f32_16x16x32_bf16 v[106:109], v[204:207], v[166:169], v[106:109]
	v_mfma_f32_16x16x32_bf16 v[78:81], v[212:215], v[166:169], v[78:81]
	v_mfma_f32_16x16x32_bf16 v[46:49], v[220:223], v[166:169], v[46:49]
	s_add_u32 m0, m0, 0x400
	v_add_u32_e32 v226, 24, v224
	v_max_i32_e32 v226, 0, v226
	v_min_i32_e32 v226, 0xffff, v226
	v_lshl_add_u32 v226, v226, 11, v231
	global_load_lds_dwordx4 v226, s[4:5]
	ds_read_b128 v[162:165], v229 offset:6144
	ds_read_b128 v[166:169], v230 offset:6144
	s_waitcnt lgkmcnt(2)
	v_mfma_f32_16x16x32_bf16 v[118:121], v[192:195], v[154:157], v[118:121]
	v_mfma_f32_16x16x32_bf16 v[98:101], v[200:203], v[154:157], v[98:101]
	v_mfma_f32_16x16x32_bf16 v[70:73], v[208:211], v[154:157], v[70:73]
	v_mfma_f32_16x16x32_bf16 v[38:41], v[216:219], v[154:157], v[38:41]
	s_add_u32 m0, m0, 0x400
	v_add_u32_e32 v226, 32, v224
	v_max_i32_e32 v226, 0, v226
	v_min_i32_e32 v226, 0xffff, v226
	v_lshl_add_u32 v226, v226, 11, v231
	global_load_lds_dwordx4 v226, s[4:5]
	v_mfma_f32_16x16x32_bf16 v[118:121], v[196:199], v[158:161], v[118:121]
	v_mfma_f32_16x16x32_bf16 v[98:101], v[204:207], v[158:161], v[98:101]
	v_mfma_f32_16x16x32_bf16 v[70:73], v[212:215], v[158:161], v[70:73]
	v_mfma_f32_16x16x32_bf16 v[38:41], v[220:223], v[158:161], v[38:41]
	s_add_u32 m0, m0, 0x400
	v_add_u32_e32 v226, 40, v224
	v_max_i32_e32 v226, 0, v226
	v_min_i32_e32 v226, 0xffff, v226
	v_lshl_add_u32 v226, v226, 11, v231
	global_load_lds_dwordx4 v226, s[4:5]
	ds_read_b128 v[154:157], v229 offset:8192
	ds_read_b128 v[158:161], v230 offset:8192
	s_waitcnt lgkmcnt(2)
	v_mfma_f32_16x16x32_bf16 v[110:113], v[192:195], v[162:165], v[110:113]
	v_mfma_f32_16x16x32_bf16 v[86:89], v[200:203], v[162:165], v[86:89]
	v_mfma_f32_16x16x32_bf16 v[54:57], v[208:211], v[162:165], v[54:57]
	v_mfma_f32_16x16x32_bf16 v[26:29], v[216:219], v[162:165], v[26:29]
	s_add_u32 m0, m0, 0x400
	v_add_u32_e32 v226, 48, v224
	v_max_i32_e32 v226, 0, v226
	v_min_i32_e32 v226, 0xffff, v226
	v_lshl_add_u32 v226, v226, 11, v231
	global_load_lds_dwordx4 v226, s[4:5]
	v_mfma_f32_16x16x32_bf16 v[110:113], v[196:199], v[166:169], v[110:113]
	v_mfma_f32_16x16x32_bf16 v[86:89], v[204:207], v[166:169], v[86:89]
	v_mfma_f32_16x16x32_bf16 v[54:57], v[212:215], v[166:169], v[54:57]
	v_mfma_f32_16x16x32_bf16 v[26:29], v[220:223], v[166:169], v[26:29]
	s_add_u32 m0, m0, 0x400
	v_add_u32_e32 v226, 56, v224
	v_max_i32_e32 v226, 0, v226
	v_min_i32_e32 v226, 0xffff, v226
	v_lshl_add_u32 v226, v226, 11, v231
	global_load_lds_dwordx4 v226, s[4:5]
	ds_read_b128 v[162:165], v229 offset:10240
	ds_read_b128 v[166:169], v230 offset:10240
	s_waitcnt lgkmcnt(2)
	v_mfma_f32_16x16x32_bf16 v[102:105], v[192:195], v[154:157], v[102:105]
	v_mfma_f32_16x16x32_bf16 v[74:77], v[200:203], v[154:157], v[74:77]
	v_mfma_f32_16x16x32_bf16 v[42:45], v[208:211], v[154:157], v[42:45]
	v_mfma_f32_16x16x32_bf16 v[18:21], v[216:219], v[154:157], v[18:21]
	s_add_u32 m0, s21, 17
	s_and_b32 m0, m0, 1
	s_lshl_b32 m0, m0, 14
	s_add_u32 m0, m0, 0x8000
	v_readfirstlane_b32 s32, v142
	s_lshl_b32 s32, s32, 2
	s_add_u32 m0, m0, s32
	v_mov_b32_e32 v226, v225
	global_load_lds_dwordx4 v226, s[22:23]
	v_mfma_f32_16x16x32_bf16 v[102:105], v[196:199], v[158:161], v[102:105]
	v_mfma_f32_16x16x32_bf16 v[74:77], v[204:207], v[158:161], v[74:77]
	v_mfma_f32_16x16x32_bf16 v[42:45], v[212:215], v[158:161], v[42:45]
	v_mfma_f32_16x16x32_bf16 v[18:21], v[220:223], v[158:161], v[18:21]
	s_add_u32 m0, m0, 0x400
	v_add_u32_e32 v226, 0x4000, v225
	global_load_lds_dwordx4 v226, s[22:23]
	ds_read_b128 v[154:157], v229 offset:12288
	ds_read_b128 v[158:161], v230 offset:12288
	s_waitcnt lgkmcnt(2)
	v_mfma_f32_16x16x32_bf16 v[90:93], v[192:195], v[162:165], v[90:93]
	v_mfma_f32_16x16x32_bf16 v[58:61], v[200:203], v[162:165], v[58:61]
	v_mfma_f32_16x16x32_bf16 v[30:33], v[208:211], v[162:165], v[30:33]
	v_mfma_f32_16x16x32_bf16 v[10:13], v[216:219], v[162:165], v[10:13]
	s_add_u32 m0, m0, 0x400
	v_add_u32_e32 v226, 0x8000, v225
	global_load_lds_dwordx4 v226, s[22:23]
	v_mfma_f32_16x16x32_bf16 v[90:93], v[196:199], v[166:169], v[90:93]
	v_mfma_f32_16x16x32_bf16 v[58:61], v[204:207], v[166:169], v[58:61]
	v_mfma_f32_16x16x32_bf16 v[30:33], v[212:215], v[166:169], v[30:33]
	v_mfma_f32_16x16x32_bf16 v[10:13], v[220:223], v[166:169], v[10:13]
	s_add_u32 m0, m0, 0x400
	v_add_u32_e32 v226, 0xc000, v225
	global_load_lds_dwordx4 v226, s[22:23]
	ds_read_b128 v[162:165], v229 offset:14336
	ds_read_b128 v[166:169], v230 offset:14336
	s_waitcnt lgkmcnt(2)
	v_mfma_f32_16x16x32_bf16 v[82:85], v[192:195], v[154:157], v[82:85]
	v_mfma_f32_16x16x32_bf16 v[50:53], v[200:203], v[154:157], v[50:53]
	v_mfma_f32_16x16x32_bf16 v[22:25], v[208:211], v[154:157], v[22:25]
	v_mfma_f32_16x16x32_bf16 v[6:9], v[216:219], v[154:157], v[6:9]
	v_mfma_f32_16x16x32_bf16 v[82:85], v[196:199], v[158:161], v[82:85]
	v_mfma_f32_16x16x32_bf16 v[50:53], v[204:207], v[158:161], v[50:53]
	v_mfma_f32_16x16x32_bf16 v[22:25], v[212:215], v[158:161], v[22:25]
	v_mfma_f32_16x16x32_bf16 v[6:9], v[220:223], v[158:161], v[6:9]
	s_waitcnt lgkmcnt(0)
	v_mfma_f32_16x16x32_bf16 v[66:69], v[192:195], v[162:165], v[66:69]
	v_mfma_f32_16x16x32_bf16 v[34:37], v[200:203], v[162:165], v[34:37]
	v_mfma_f32_16x16x32_bf16 v[14:17], v[208:211], v[162:165], v[14:17]
	v_mfma_f32_16x16x32_bf16 v[2:5], v[216:219], v[162:165], v[2:5]
	v_mfma_f32_16x16x32_bf16 v[66:69], v[196:199], v[166:169], v[66:69]
	v_mfma_f32_16x16x32_bf16 v[34:37], v[204:207], v[166:169], v[34:37]
	v_mfma_f32_16x16x32_bf16 v[14:17], v[212:215], v[166:169], v[14:17]
	v_mfma_f32_16x16x32_bf16 v[2:5], v[220:223], v[166:169], v[2:5]
	v_xor_b32_e32 v229, 0x4000, v229
	v_xor_b32_e32 v230, 0x4000, v230
	s_add_i32 s21, s21, 1
	s_cmp_lg_u32 s21, 15
	s_cbranch_scc1 .Lbk64_418
	s_waitcnt vmcnt(0)
	s_barrier
	ds_read_b128 v[192:195], v227
	ds_read_b128 v[196:199], v228
	ds_read_b128 v[200:203], v227 offset:2048
	ds_read_b128 v[204:207], v228 offset:2048
	ds_read_b128 v[208:211], v227 offset:4096
	ds_read_b128 v[212:215], v228 offset:4096
	ds_read_b128 v[216:219], v227 offset:6144
	ds_read_b128 v[220:223], v228 offset:6144
	s_waitcnt lgkmcnt(0)
	s_barrier
	ds_read_b128 v[154:157], v229 offset:0
	ds_read_b128 v[158:161], v230 offset:0
	ds_read_b128 v[162:165], v229 offset:2048
	ds_read_b128 v[166:169], v230 offset:2048
	s_waitcnt lgkmcnt(2)
	v_mfma_f32_16x16x32_bf16 v[126:129], v[192:195], v[154:157], v[126:129]
	v_mfma_f32_16x16x32_bf16 v[114:117], v[200:203], v[154:157], v[114:117]
	v_mfma_f32_16x16x32_bf16 v[94:97], v[208:211], v[154:157], v[94:97]
	v_mfma_f32_16x16x32_bf16 v[62:65], v[216:219], v[154:157], v[62:65]
	v_mfma_f32_16x16x32_bf16 v[126:129], v[196:199], v[158:161], v[126:129]
	v_mfma_f32_16x16x32_bf16 v[114:117], v[204:207], v[158:161], v[114:117]
	v_mfma_f32_16x16x32_bf16 v[94:97], v[212:215], v[158:161], v[94:97]
	v_mfma_f32_16x16x32_bf16 v[62:65], v[220:223], v[158:161], v[62:65]
	ds_read_b128 v[154:157], v229 offset:4096
	ds_read_b128 v[158:161], v230 offset:4096
	s_waitcnt lgkmcnt(2)
	v_mfma_f32_16x16x32_bf16 v[122:125], v[192:195], v[162:165], v[122:125]
	v_mfma_f32_16x16x32_bf16 v[106:109], v[200:203], v[162:165], v[106:109]
	v_mfma_f32_16x16x32_bf16 v[78:81], v[208:211], v[162:165], v[78:81]
	v_mfma_f32_16x16x32_bf16 v[46:49], v[216:219], v[162:165], v[46:49]
	v_mfma_f32_16x16x32_bf16 v[122:125], v[196:199], v[166:169], v[122:125]
	v_mfma_f32_16x16x32_bf16 v[106:109], v[204:207], v[166:169], v[106:109]
	v_mfma_f32_16x16x32_bf16 v[78:81], v[212:215], v[166:169], v[78:81]
	v_mfma_f32_16x16x32_bf16 v[46:49], v[220:223], v[166:169], v[46:49]
	ds_read_b128 v[162:165], v229 offset:6144
	ds_read_b128 v[166:169], v230 offset:6144
	s_waitcnt lgkmcnt(2)
	v_mfma_f32_16x16x32_bf16 v[118:121], v[192:195], v[154:157], v[118:121]
	v_mfma_f32_16x16x32_bf16 v[98:101], v[200:203], v[154:157], v[98:101]
	v_mfma_f32_16x16x32_bf16 v[70:73], v[208:211], v[154:157], v[70:73]
	v_mfma_f32_16x16x32_bf16 v[38:41], v[216:219], v[154:157], v[38:41]
	v_mfma_f32_16x16x32_bf16 v[118:121], v[196:199], v[158:161], v[118:121]
	v_mfma_f32_16x16x32_bf16 v[98:101], v[204:207], v[158:161], v[98:101]
	v_mfma_f32_16x16x32_bf16 v[70:73], v[212:215], v[158:161], v[70:73]
	v_mfma_f32_16x16x32_bf16 v[38:41], v[220:223], v[158:161], v[38:41]
	ds_read_b128 v[154:157], v229 offset:8192
	ds_read_b128 v[158:161], v230 offset:8192
	s_waitcnt lgkmcnt(2)
	v_mfma_f32_16x16x32_bf16 v[110:113], v[192:195], v[162:165], v[110:113]
	v_mfma_f32_16x16x32_bf16 v[86:89], v[200:203], v[162:165], v[86:89]
	v_mfma_f32_16x16x32_bf16 v[54:57], v[208:211], v[162:165], v[54:57]
	v_mfma_f32_16x16x32_bf16 v[26:29], v[216:219], v[162:165], v[26:29]
	v_mfma_f32_16x16x32_bf16 v[110:113], v[196:199], v[166:169], v[110:113]
	v_mfma_f32_16x16x32_bf16 v[86:89], v[204:207], v[166:169], v[86:89]
	v_mfma_f32_16x16x32_bf16 v[54:57], v[212:215], v[166:169], v[54:57]
	v_mfma_f32_16x16x32_bf16 v[26:29], v[220:223], v[166:169], v[26:29]
	ds_read_b128 v[162:165], v229 offset:10240
	ds_read_b128 v[166:169], v230 offset:10240
	s_waitcnt lgkmcnt(2)
	v_mfma_f32_16x16x32_bf16 v[102:105], v[192:195], v[154:157], v[102:105]
	v_mfma_f32_16x16x32_bf16 v[74:77], v[200:203], v[154:157], v[74:77]
	v_mfma_f32_16x16x32_bf16 v[42:45], v[208:211], v[154:157], v[42:45]
	v_mfma_f32_16x16x32_bf16 v[18:21], v[216:219], v[154:157], v[18:21]
	v_mfma_f32_16x16x32_bf16 v[102:105], v[196:199], v[158:161], v[102:105]
	v_mfma_f32_16x16x32_bf16 v[74:77], v[204:207], v[158:161], v[74:77]
	v_mfma_f32_16x16x32_bf16 v[42:45], v[212:215], v[158:161], v[42:45]
	v_mfma_f32_16x16x32_bf16 v[18:21], v[220:223], v[158:161], v[18:21]
	ds_read_b128 v[154:157], v229 offset:12288
	ds_read_b128 v[158:161], v230 offset:12288
	s_waitcnt lgkmcnt(2)
	v_mfma_f32_16x16x32_bf16 v[90:93], v[192:195], v[162:165], v[90:93]
	v_mfma_f32_16x16x32_bf16 v[58:61], v[200:203], v[162:165], v[58:61]
	v_mfma_f32_16x16x32_bf16 v[30:33], v[208:211], v[162:165], v[30:33]
	v_mfma_f32_16x16x32_bf16 v[10:13], v[216:219], v[162:165], v[10:13]
	v_mfma_f32_16x16x32_bf16 v[90:93], v[196:199], v[166:169], v[90:93]
	v_mfma_f32_16x16x32_bf16 v[58:61], v[204:207], v[166:169], v[58:61]
	v_mfma_f32_16x16x32_bf16 v[30:33], v[212:215], v[166:169], v[30:33]
	v_mfma_f32_16x16x32_bf16 v[10:13], v[220:223], v[166:169], v[10:13]
	ds_read_b128 v[162:165], v229 offset:14336
	ds_read_b128 v[166:169], v230 offset:14336
	s_waitcnt lgkmcnt(2)
	v_mfma_f32_16x16x32_bf16 v[82:85], v[192:195], v[154:157], v[82:85]
	v_mfma_f32_16x16x32_bf16 v[50:53], v[200:203], v[154:157], v[50:53]
	v_mfma_f32_16x16x32_bf16 v[22:25], v[208:211], v[154:157], v[22:25]
	v_mfma_f32_16x16x32_bf16 v[6:9], v[216:219], v[154:157], v[6:9]
	v_mfma_f32_16x16x32_bf16 v[82:85], v[196:199], v[158:161], v[82:85]
	v_mfma_f32_16x16x32_bf16 v[50:53], v[204:207], v[158:161], v[50:53]
	v_mfma_f32_16x16x32_bf16 v[22:25], v[212:215], v[158:161], v[22:25]
	v_mfma_f32_16x16x32_bf16 v[6:9], v[220:223], v[158:161], v[6:9]
	s_waitcnt lgkmcnt(0)
	v_mfma_f32_16x16x32_bf16 v[66:69], v[192:195], v[162:165], v[66:69]
	v_mfma_f32_16x16x32_bf16 v[34:37], v[200:203], v[162:165], v[34:37]
	v_mfma_f32_16x16x32_bf16 v[14:17], v[208:211], v[162:165], v[14:17]
	v_mfma_f32_16x16x32_bf16 v[2:5], v[216:219], v[162:165], v[2:5]
	v_mfma_f32_16x16x32_bf16 v[66:69], v[196:199], v[166:169], v[66:69]
	v_mfma_f32_16x16x32_bf16 v[34:37], v[204:207], v[166:169], v[34:37]
	v_mfma_f32_16x16x32_bf16 v[14:17], v[212:215], v[166:169], v[14:17]
	v_mfma_f32_16x16x32_bf16 v[2:5], v[220:223], v[166:169], v[2:5]
	s_nop 7
	s_nop 7
	s_waitcnt vmcnt(6)
	v_add_u32_e32 v142, v149, v147
	s_waitcnt lgkmcnt(0)
	v_and_b32_e32 v1, 0xfffffc0, v1
	v_lshl_or_b32 v1, v144, 2, v1
	v_mul_lo_u32 v1, v1, s33
	v_lshl_or_b32 v1, v143, 2, v1
	s_waitcnt lgkmcnt(0)
	s_waitcnt lgkmcnt(0)
	s_waitcnt lgkmcnt(0)
	s_waitcnt lgkmcnt(0)
	s_waitcnt lgkmcnt(0)
	v_mov_b64_e32 v[162:163], v[30:31]
	v_mov_b64_e32 v[164:165], v[32:33]
	v_mov_b64_e32 v[134:135], v[10:11]
	v_mov_b64_e32 v[136:137], v[12:13]
	s_nop 2
	s_waitcnt lgkmcnt(0)
	v_mov_b64_e32 v[180:181], v[6:7]
	v_mov_b64_e32 v[182:183], v[8:9]
	s_nop 2
	s_waitcnt vmcnt(0)
	v_mov_b64_e32 v[166:167], v[22:23]
	v_mov_b64_e32 v[168:169], v[24:25]
	s_waitcnt lgkmcnt(0)
	v_mov_b64_e32 v[130:131], v[34:35]
	v_mov_b64_e32 v[132:133], v[36:37]
	v_mov_b64_e32 v[138:139], v[14:15]
	v_mov_b64_e32 v[140:141], v[16:17]
	v_mov_b64_e32 v[158:159], v[2:3]
	v_mov_b64_e32 v[160:161], v[4:5]
	s_nop 1
	s_waitcnt lgkmcnt(0)
	v_mov_b64_e32 v[22:23], v[126:127]
	v_mov_b64_e32 v[24:25], v[128:129]
	s_nop 2
	v_mov_b64_e32 v[32:33], v[114:115]
	v_mov_b64_e32 v[34:35], v[116:117]
	s_nop 2
	s_waitcnt lgkmcnt(0)
	v_mov_b64_e32 v[2:3], v[122:123]
	v_mov_b64_e32 v[4:5], v[124:125]
	v_mov_b64_e32 v[122:123], v[46:47]
	v_mov_b64_e32 v[124:125], v[48:49]
	s_waitcnt lgkmcnt(0)
	v_mov_b64_e32 v[46:47], v[118:119]
	v_mov_b64_e32 v[48:49], v[120:121]
	v_mov_b64_e32 v[118:119], v[38:39]
	v_mov_b64_e32 v[120:121], v[40:41]
	v_mov_b64_e32 v[36:37], v[110:111]
	v_mov_b64_e32 v[38:39], v[112:113]
	s_nop 2
	s_waitcnt vmcnt(0) lgkmcnt(0)
	s_barrier
	ds_write2_b32 v1, v22, v2 offset1:16
	ds_write2_b32 v1, v23, v3 offset0:68 offset1:84
	ds_write2_b32 v1, v24, v4 offset0:136 offset1:152
	ds_write2_b32 v1, v25, v5 offset0:204 offset1:220
	ds_write2_b32 v1, v46, v36 offset0:32 offset1:48
	ds_write2_b32 v1, v47, v37 offset0:100 offset1:116
	ds_write2_b32 v1, v48, v38 offset0:168 offset1:184
	ds_write2_b32 v1, v49, v39 offset0:236 offset1:252
	v_mov_b64_e32 v[200:201], v[86:87]
	v_mov_b64_e32 v[202:203], v[88:89]
	s_nop 1
	v_add_u32_e32 v88, 0x1000, v1
	ds_write2_b32 v88, v32, v106 offset0:64 offset1:80
	ds_write2_b32 v88, v33, v107 offset0:132 offset1:148
	ds_write2_b32 v88, v34, v108 offset0:200 offset1:216
	v_add_u32_e32 v89, 0x1400, v1
	v_mov_b64_e32 v[212:213], v[26:27]
	v_mov_b64_e32 v[214:215], v[28:29]
	ds_write2_b32 v89, v35, v109 offset0:12 offset1:28
	ds_write2_b32 v88, v98, v200 offset0:96 offset1:112
	ds_write2_b32 v88, v99, v201 offset0:164 offset1:180
	ds_write2_b32 v88, v100, v202 offset0:232 offset1:248
	ds_write2_b32 v89, v101, v203 offset0:44 offset1:60
	v_mov_b64_e32 v[30:31], v[90:91]
	v_mov_b64_e32 v[32:33], v[92:93]
	s_nop 2
	v_add_u32_e32 v90, 0x2000, v1
	v_add_u32_e32 v91, 0x2400, v1
	ds_write2_b32 v90, v94, v78 offset0:128 offset1:144
	ds_write2_b32 v90, v95, v79 offset0:196 offset1:212
	ds_write2_b32 v91, v96, v80 offset0:8 offset1:24
	ds_write2_b32 v91, v97, v81 offset0:76 offset1:92
	ds_write2_b32 v90, v70, v54 offset0:160 offset1:176
	ds_write2_b32 v90, v71, v55 offset0:228 offset1:244
	ds_write2_b32 v91, v72, v56 offset0:40 offset1:56
	v_add_u32_e32 v92, 0x3000, v1
	v_add_u32_e32 v93, 0x3400, v1
	v_mov_b32_e32 v70, v170
	v_mov_b64_e32 v[6:7], v[42:43]
	v_mov_b64_e32 v[8:9], v[44:45]
	ds_write2_b32 v91, v73, v57 offset0:108 offset1:124
	ds_write2_b32 v92, v62, v122 offset0:192 offset1:208
	ds_write2_b32 v93, v63, v123 offset0:4 offset1:20
	ds_write2_b32 v93, v64, v124 offset0:72 offset1:88
	v_mov_b64_e32 v[42:43], v[50:51]
	v_mov_b64_e32 v[44:45], v[52:53]
	ds_write2_b32 v93, v65, v125 offset0:140 offset1:156
	ds_write2_b32 v92, v118, v212 offset0:224 offset1:240
	ds_write2_b32 v93, v119, v213 offset0:36 offset1:52
	ds_write2_b32 v93, v120, v214 offset0:104 offset1:120
	ds_write2_b32 v93, v121, v215 offset0:172 offset1:188
	s_waitcnt lgkmcnt(0)
	s_barrier
	v_mov_b64_e32 v[14:15], v[102:103]
	v_mov_b64_e32 v[16:17], v[104:105]
	v_ashrrev_i32_e32 v50, 7, v70
	v_mov_b64_e32 v[10:11], v[74:75]
	v_mov_b64_e32 v[12:13], v[76:77]
	v_mov_b64_e32 v[2:3], v[18:19]
	v_mov_b64_e32 v[4:5], v[20:21]
	v_mov_b64_e32 v[26:27], v[58:59]
	v_mov_b64_e32 v[28:29], v[60:61]
	v_mov_b64_e32 v[22:23], v[162:163]
	v_mov_b64_e32 v[24:25], v[164:165]
	v_mov_b64_e32 v[18:19], v[134:135]
	v_mov_b64_e32 v[20:21], v[136:137]
	v_mov_b64_e32 v[46:47], v[82:83]
	v_mov_b64_e32 v[48:49], v[84:85]
	v_mov_b64_e32 v[38:39], v[166:167]
	v_mov_b64_e32 v[40:41], v[168:169]
	v_mov_b64_e32 v[34:35], v[180:181]
	v_mov_b64_e32 v[36:37], v[182:183]
	v_mov_b64_e32 v[62:63], v[66:67]
	v_mov_b64_e32 v[64:65], v[68:69]
	v_mov_b64_e32 v[58:59], v[130:131]
	v_mov_b64_e32 v[60:61], v[132:133]
	s_nop 1
	v_add_u32_e32 v66, s46, v50
	v_cmp_lt_i32_e32 vcc, s91, v66
	v_mov_b64_e32 v[54:55], v[138:139]
	v_mov_b64_e32 v[56:57], v[140:141]
	v_mov_b64_e32 v[50:51], v[158:159]
	v_mov_b64_e32 v[52:53], v[160:161]
	s_and_saveexec_b64 s[4:5], vcc
	s_xor_b64 s[22:23], exec, s[4:5]
	v_add_u32_e32 v66, 0xfffffef0, v66
	v_mul_hi_u32 v67, v66, s96
	v_lshrrev_b32_e32 v67, 3, v67
	v_add_u32_e32 v68, 16, v67
	v_lshl_add_u32 v67, v67, 5, v67
	v_sub_u32_e32 v71, v66, v67
	s_or_saveexec_b64 s[22:23], s[22:23]
	v_mov_b32_e32 v72, 0x1000
	s_xor_b64 exec, exec, s[22:23]
	v_mul_hi_i32 v67, v66, s97
	v_lshrrev_b32_e32 v68, 31, v67
	v_ashrrev_i32_e32 v67, 3, v67
	v_add_u32_e32 v68, v67, v68
	v_lshl_add_u32 v67, v68, 4, v68
	v_sub_u32_e32 v71, v66, v67
	v_mov_b32_e32 v72, 0x800
	s_or_b64 exec, exec, s[22:23]
	v_cmp_lt_i32_e32 vcc, 15, v68
	s_and_saveexec_b64 s[4:5], vcc
	s_xor_b64 s[4:5], exec, s[4:5]
	v_add_u32_e32 v66, -16, v68
	v_mov_b32_e32 v67, v0
	v_lshlrev_b64 v[66:67], 12, v[66:67]
	v_lshl_add_u64 v[66:67], v[66:67], 0, s[42:43]
	s_andn2_saveexec_b64 s[22:23], s[4:5]
	v_ashrrev_i32_e32 v69, 31, v68
	v_lshlrev_b64 v[66:67], 11, v[68:69]
	s_or_b64 exec, exec, s[22:23]
	v_and_b32_e32 v69, 0x7f, v70
	v_cmp_gt_i32_e32 vcc, s79, v69
	s_and_saveexec_b64 s[22:23], vcc
	s_cbranch_execz .LBB0_436
	v_cmp_ne_u32_e32 vcc, 0, v69
	s_and_b64 exec, exec, vcc
	s_cbranch_execz .LBB0_436
	v_mul_lo_u32 v71, v71, s54
	v_add3_u32 v68, v69, v71, -1
	v_cmp_lt_i32_e32 vcc, v68, v72
	s_and_b64 exec, exec, vcc
	s_cbranch_execz .LBB0_436
	v_cmp_lt_i32_e32 vcc, 0, v68
	v_mov_b32_e32 v83, 0
	v_mov_b32_e32 v82, 0
	s_and_saveexec_b64 s[4:5], vcc
	v_mov_b32_e32 v73, 0x11ffc
	v_lshl_add_u32 v73, v70, 2, v73
	ds_read_b32 v82, v73
	s_or_b64 exec, exec, s[4:5]
	v_add_u32_e32 v69, v71, v69
	v_cmp_lt_i32_e32 vcc, v69, v72
	v_lshl_add_u32 v69, v70, 2, v175
	ds_read_b32 v84, v69
	s_and_saveexec_b64 s[4:5], vcc
	ds_read_b32 v83, v69 offset:4
	s_or_b64 exec, exec, s[4:5]
	s_lshl_b32 s4, s20, 6
	s_ashr_i32 s5, s4, 31
	s_lshl_b64 s[4:5], s[4:5], 1
	v_ashrrev_i32_e32 v69, 31, v68
	s_add_u32 s4, s38, s4
	v_lshl_add_u64 v[66:67], v[66:67], 0, v[68:69]
	v_mul_lo_u32 v68, v70, s33
	s_addc_u32 s5, s39, s5
	v_add_u32_e32 v94, 0xfffffef0, v68
	v_mov_b64_e32 v[68:69], s[4:5]
	v_mad_u64_u32 v[86:87], s[4:5], v66, s3, v[68:69]
	v_mov_b32_e32 v66, v87
	v_mad_u64_u32 v[66:67], s[4:5], v67, s3, v[66:67]
	v_mov_b32_e32 v87, v66
	s_mov_b32 s4, 0
	v_add_u32_e32 v251, 0x190, v94
.LBB0_435:
	s_add_i32 s5, s4, 0x12440
	v_add_u32_e32 v95, s4, v94
	v_mov_b32_e32 v85, s5
	s_add_i32 s5, s4, 0x12540
	ds_read_b128 v[70:73], v95
	ds_read_b128 v[66:69], v95 offset:16
	ds_read_b128 v[74:77], v95 offset:272
	ds_read_b128 v[78:81], v95 offset:544
	ds_read_b128 v[96:99], v95 offset:400
	ds_read_b128 v[100:103], v85
	v_mov_b32_e32 v85, s5
	s_add_i32 s5, s4, 0x12640
	ds_read_b128 v[104:107], v85
	v_mov_b32_e32 v85, s5
	ds_read_b128 v[108:111], v85
	s_add_i32 s5, s4, 0x12740
	v_mov_b32_e32 v85, s5
	ds_read_b128 v[112:115], v85
	s_waitcnt lgkmcnt(0)
	v_mov_b32_e32 v116, v70
	s_waitcnt lgkmcnt(5)
	v_mov_b32_e32 v117, v78
	v_pk_mul_f32 v[116:117], v[82:83], v[116:117]
	s_waitcnt lgkmcnt(3)
	v_mov_b32_e32 v118, v100
	s_waitcnt lgkmcnt(1)
	v_mov_b32_e32 v119, v108
	v_mul_f32_e32 v74, v84, v74
	v_pk_mul_f32 v[116:117], v[116:117], v[118:119]
	v_mov_b32_e32 v78, v71
	v_fma_f32 v70, v74, v104, v116
	v_add_f32_e32 v70, v70, v117
	s_waitcnt lgkmcnt(0)
	v_add_f32_e32 v85, v70, v112
	v_mul_f32_e32 v70, 0xbfb8aa3b, v85
	v_exp_f32_e32 v70, v70
	v_mov_b32_e32 v108, v101
	v_mul_f32_e32 v74, v84, v75
	v_mov_b32_e32 v116, v96
	v_add_f32_e32 v70, 1.0, v70
	v_rcp_f32_e32 v117, v70
	v_pk_mul_f32 v[70:71], v[82:83], v[78:79]
	v_mov_b32_e32 v75, v110
	v_pk_mul_f32 v[70:71], v[70:71], v[108:109]
	v_pk_mul_f32 v[116:117], v[84:85], v[116:117]
	v_fma_f32 v70, v74, v105, v70
	v_add_f32_e32 v70, v70, v71
	v_add_f32_e32 v85, v70, v113
	v_mul_f32_e32 v70, 0xbfb8aa3b, v85
	v_exp_f32_e32 v70, v70
	v_mul_f32_e32 v116, v116, v117
	v_mov_b32_e32 v74, v102
	v_mul_f32_e32 v76, v84, v76
	v_add_f32_e32 v70, 1.0, v70
	v_rcp_f32_e32 v71, v70
	v_mov_b32_e32 v70, v97
	v_mov_b32_e32 v110, v103
	s_add_i32 s5, s4, 0x12450
	v_pk_mul_f32 v[70:71], v[84:85], v[70:71]
	v_mov_b32_e32 v112, v66
	v_mul_f32_e32 v117, v70, v71
	v_mov_b32_e32 v70, v72
	v_mov_b32_e32 v71, v80
	v_pk_mul_f32 v[70:71], v[82:83], v[70:71]
	v_mov_b32_e32 v80, v73
	v_pk_mul_f32 v[70:71], v[70:71], v[74:75]
	v_mul_f32_e32 v72, v84, v77
	v_fma_f32 v70, v76, v106, v70
	v_add_f32_e32 v70, v70, v71
	v_add_f32_e32 v85, v70, v114
	v_mul_f32_e32 v70, 0xbfb8aa3b, v85
	v_exp_f32_e32 v70, v70
	s_nop 0
	v_add_f32_e32 v70, 1.0, v70
	v_rcp_f32_e32 v71, v70
	v_mov_b32_e32 v70, v98
	v_pk_mul_f32 v[70:71], v[84:85], v[70:71]
	s_nop 0
	v_mul_f32_e32 v118, v70, v71
	v_pk_mul_f32 v[70:71], v[82:83], v[80:81]
	s_nop 0
	v_pk_mul_f32 v[70:71], v[70:71], v[110:111]
	s_nop 0
	v_fma_f32 v70, v72, v107, v70
	v_add_f32_e32 v70, v70, v71
	v_add_f32_e32 v85, v70, v115
	v_mul_f32_e32 v70, 0xbfb8aa3b, v85
	v_exp_f32_e32 v70, v70
	s_nop 0
	v_add_f32_e32 v70, 1.0, v70
	v_rcp_f32_e32 v71, v70
	v_mov_b32_e32 v70, v99
	v_pk_mul_f32 v[70:71], v[84:85], v[70:71]
	v_mov_b32_e32 v85, s5
	s_add_i32 s5, s4, 0x12550
	v_mul_f32_e32 v119, v70, v71
	ds_read_b128 v[78:81], v95 offset:288
	ds_read_b128 v[74:77], v95 offset:560
	ds_read_b128 v[70:73], v95 offset:416
	ds_read_b128 v[96:99], v85
	v_mov_b32_e32 v85, s5
	s_add_i32 s5, s4, 0x12650
	ds_read_b128 v[100:103], v85
	v_mov_b32_e32 v85, s5
	ds_read_b128 v[104:107], v85
	s_add_i32 s5, s4, 0x12750
	v_mov_b32_e32 v85, s5
	ds_read_b128 v[108:111], v85
	s_waitcnt lgkmcnt(0)
	v_mov_b32_e32 v113, v74
	v_pk_mul_f32 v[112:113], v[82:83], v[112:113]
	s_waitcnt lgkmcnt(3)
	v_mov_b32_e32 v114, v96
	s_waitcnt lgkmcnt(1)
	v_mov_b32_e32 v115, v104
	v_mul_f32_e32 v78, v84, v78
	v_pk_mul_f32 v[112:113], v[112:113], v[114:115]
	v_mov_b32_e32 v74, v67
	v_fma_f32 v66, v78, v100, v112
	v_add_f32_e32 v66, v66, v113
	s_waitcnt lgkmcnt(0)
	v_add_f32_e32 v85, v66, v108
	v_mul_f32_e32 v66, 0xbfb8aa3b, v85
	v_exp_f32_e32 v66, v66
	v_mov_b32_e32 v104, v97
	v_mov_b32_e32 v112, v70
	v_mul_f32_e32 v70, v84, v79
	v_add_f32_e32 v66, 1.0, v66
	v_rcp_f32_e32 v113, v66
	v_pk_mul_f32 v[66:67], v[82:83], v[74:75]
	v_mul_f32_e32 v75, v84, v80
	v_pk_mul_f32 v[66:67], v[66:67], v[104:105]
	v_pk_mul_f32 v[112:113], v[84:85], v[112:113]
	v_fma_f32 v66, v70, v101, v66
	v_add_f32_e32 v66, v66, v67
	v_add_f32_e32 v85, v66, v109
	v_mul_f32_e32 v66, 0xbfb8aa3b, v85
	v_exp_f32_e32 v66, v66
	v_mov_b32_e32 v70, v98
	s_add_i32 s4, s4, 32
	v_mul_f32_e32 v78, v112, v113
	v_add_f32_e32 v66, 1.0, v66
	v_rcp_f32_e32 v67, v66
	v_mov_b32_e32 v66, v71
	v_mov_b32_e32 v71, v106
	v_mov_b32_e32 v106, v99
	v_pk_mul_f32 v[66:67], v[84:85], v[66:67]
	s_cmpk_lg_i32 s4, 0x80
	v_mul_f32_e32 v74, v66, v67
	v_mov_b32_e32 v66, v68
	v_mov_b32_e32 v67, v76
	v_pk_mul_f32 v[66:67], v[82:83], v[66:67]
	v_mov_b32_e32 v76, v69
	v_pk_mul_f32 v[66:67], v[66:67], v[70:71]
	v_mul_f32_e32 v68, v84, v81
	v_fma_f32 v66, v75, v102, v66
	v_add_f32_e32 v66, v66, v67
	v_add_f32_e32 v85, v66, v110
	v_mul_f32_e32 v66, 0xbfb8aa3b, v85
	v_exp_f32_e32 v66, v66
	s_nop 0
	v_add_f32_e32 v66, 1.0, v66
	v_rcp_f32_e32 v67, v66
	v_mov_b32_e32 v66, v72
	v_pk_mul_f32 v[66:67], v[84:85], v[66:67]
	s_nop 0
	v_mul_f32_e32 v70, v66, v67
	v_pk_mul_f32 v[66:67], v[82:83], v[76:77]
	s_nop 0
	v_pk_mul_f32 v[66:67], v[66:67], v[106:107]
	s_nop 0
	v_fma_f32 v66, v68, v103, v66
	v_add_f32_e32 v66, v66, v67
	v_add_f32_e32 v85, v66, v111
	v_mul_f32_e32 v66, 0xbfb8aa3b, v85
	v_exp_f32_e32 v66, v66
	v_cvt_pk_bf16_f32 v68, v78, v74
	s_nop 0
	v_add_f32_e32 v66, 1.0, v66
	v_rcp_f32_e32 v67, v66
	v_mov_b32_e32 v66, v73
	v_pk_mul_f32 v[66:67], v[84:85], v[66:67]
	s_nop 0
	v_mul_f32_e32 v69, v66, v67
	v_cvt_pk_bf16_f32 v66, v116, v117
	v_cvt_pk_bf16_f32 v67, v118, v119
	v_cvt_pk_bf16_f32 v69, v70, v69
	ds_write_b128 v251, v[66:69]
	v_lshl_add_u64 v[86:87], v[86:87], 0, 16
	v_add_u32_e32 v251, 16, v251
	s_cbranch_scc1 .LBB0_435
.LBB0_436:
	s_mov_b64 vcc, exec
	s_cmp_eq_u64 vcc, 0
	s_cbranch_scc1 .Lup_skip_p0
	v_readfirstlane_b32 s4, v86
	v_readfirstlane_b32 s5, v87
	s_ff1_i32_b64 s32, vcc
	s_or_b64 exec, exec, s[22:23]
	v_and_b32_e32 v242, 63, v170
	v_lshrrev_b32_e32 v243, 2, v242
	v_and_b32_e32 v244, 3, v242
	v_lshlrev_b32_e32 v244, 4, v244
	v_sub_u32_e32 v245, v170, v242
	v_add_u32_e32 v245, s32, v245
	v_mul_u32_u24_e32 v245, 0x110, v245
	v_add_u32_e32 v245, v245, v244
	v_add_u32_e32 v245, 0x80, v245
	s_waitcnt lgkmcnt(0)
	v_add_u32_e32 v246, 0, v243
	v_lshrrev_b64 v[236:237], v246, vcc
	v_and_b32_e32 v236, 1, v236
	v_subrev_u32_e32 v246, s32, v246
	v_mul_i32_i24_e32 v246, v246, v236
	v_mul_i32_i24_e32 v238, 0x110, v246
	v_add_u32_e32 v238, v238, v245
	ds_read_b128 v[232:235], v238
	v_mul_i32_i24_e32 v238, 0x1580, v246
	v_add_u32_e32 v238, v238, v244
	v_add_u32_e32 v238, 0xffffffc0, v238
	v_ashrrev_i32_e32 v239, 31, v238
	v_lshl_add_u64 v[240:241], v[238:239], 0, s[4:5]
	s_waitcnt lgkmcnt(0)
	global_store_dwordx4 v[240:241], v[232:235], off
	s_nop 1
	v_add_u32_e32 v246, 16, v243
	v_lshrrev_b64 v[236:237], v246, vcc
	v_and_b32_e32 v236, 1, v236
	v_subrev_u32_e32 v246, s32, v246
	v_mul_i32_i24_e32 v246, v246, v236
	v_mul_i32_i24_e32 v238, 0x110, v246
	v_add_u32_e32 v238, v238, v245
	ds_read_b128 v[232:235], v238
	v_mul_i32_i24_e32 v238, 0x1580, v246
	v_add_u32_e32 v238, v238, v244
	v_add_u32_e32 v238, 0xffffffc0, v238
	v_ashrrev_i32_e32 v239, 31, v238
	v_lshl_add_u64 v[240:241], v[238:239], 0, s[4:5]
	s_waitcnt lgkmcnt(0)
	global_store_dwordx4 v[240:241], v[232:235], off
	s_nop 1
	v_add_u32_e32 v246, 32, v243
	v_lshrrev_b64 v[236:237], v246, vcc
	v_and_b32_e32 v236, 1, v236
	v_subrev_u32_e32 v246, s32, v246
	v_mul_i32_i24_e32 v246, v246, v236
	v_mul_i32_i24_e32 v238, 0x110, v246
	v_add_u32_e32 v238, v238, v245
	ds_read_b128 v[232:235], v238
	v_mul_i32_i24_e32 v238, 0x1580, v246
	v_add_u32_e32 v238, v238, v244
	v_add_u32_e32 v238, 0xffffffc0, v238
	v_ashrrev_i32_e32 v239, 31, v238
	v_lshl_add_u64 v[240:241], v[238:239], 0, s[4:5]
	s_waitcnt lgkmcnt(0)
	global_store_dwordx4 v[240:241], v[232:235], off
	s_nop 1
	v_add_u32_e32 v246, 48, v243
	v_lshrrev_b64 v[236:237], v246, vcc
	v_and_b32_e32 v236, 1, v236
	v_subrev_u32_e32 v246, s32, v246
	v_mul_i32_i24_e32 v246, v246, v236
	v_mul_i32_i24_e32 v238, 0x110, v246
	v_add_u32_e32 v238, v238, v245
	ds_read_b128 v[232:235], v238
	v_mul_i32_i24_e32 v238, 0x1580, v246
	v_add_u32_e32 v238, v238, v244
	v_add_u32_e32 v238, 0xffffffc0, v238
	v_ashrrev_i32_e32 v239, 31, v238
	v_lshl_add_u64 v[240:241], v[238:239], 0, s[4:5]
	s_waitcnt lgkmcnt(0)
	global_store_dwordx4 v[240:241], v[232:235], off
	s_nop 1
.Lup_skip_p0:
	s_or_b64 exec, exec, s[22:23]
	s_waitcnt lgkmcnt(0)
	s_barrier
	ds_write2_b32 v1, v14, v30 offset1:16
	ds_write2_b32 v1, v15, v31 offset0:68 offset1:84
	ds_write2_b32 v1, v16, v32 offset0:136 offset1:152
	ds_write2_b32 v1, v17, v33 offset0:204 offset1:220
	ds_write2_b32 v1, v46, v62 offset0:32 offset1:48
	ds_write2_b32 v1, v47, v63 offset0:100 offset1:116
	ds_write2_b32 v1, v48, v64 offset0:168 offset1:184
	ds_write2_b32 v1, v49, v65 offset0:236 offset1:252
	ds_write2_b32 v88, v10, v26 offset0:64 offset1:80
	ds_write2_b32 v88, v11, v27 offset0:132 offset1:148
	ds_write2_b32 v88, v12, v28 offset0:200 offset1:216
	ds_write2_b32 v89, v13, v29 offset0:12 offset1:28
	ds_write2_b32 v88, v42, v58 offset0:96 offset1:112
	ds_write2_b32 v88, v43, v59 offset0:164 offset1:180
	ds_write2_b32 v88, v44, v60 offset0:232 offset1:248
	ds_write2_b32 v89, v45, v61 offset0:44 offset1:60
	ds_write2_b32 v90, v6, v22 offset0:128 offset1:144
	ds_write2_b32 v90, v7, v23 offset0:196 offset1:212
	ds_write2_b32 v91, v8, v24 offset0:8 offset1:24
	ds_write2_b32 v91, v9, v25 offset0:76 offset1:92
	ds_write2_b32 v90, v38, v54 offset0:160 offset1:176
	ds_write2_b32 v90, v39, v55 offset0:228 offset1:244
	ds_write2_b32 v91, v40, v56 offset0:40 offset1:56
	ds_write2_b32 v91, v41, v57 offset0:108 offset1:124
	ds_write2_b32 v92, v2, v18 offset0:192 offset1:208
	ds_write2_b32 v93, v3, v19 offset0:4 offset1:20
	ds_write2_b32 v93, v4, v20 offset0:72 offset1:88
	ds_write2_b32 v93, v5, v21 offset0:140 offset1:156
	ds_write2_b32 v92, v34, v50 offset0:224 offset1:240
	ds_write2_b32 v93, v35, v51 offset0:36 offset1:52
	ds_write2_b32 v93, v36, v52 offset0:104 offset1:120
	ds_write2_b32 v93, v37, v53 offset0:172 offset1:188
	v_mov_b32_e32 v1, v170
	s_waitcnt lgkmcnt(0)
	s_barrier
	s_nop 0
	v_ashrrev_i32_e32 v2, 7, v1
	v_add_u32_e32 v2, s46, v2
	v_cmp_lt_i32_e32 vcc, s91, v2
	s_and_saveexec_b64 s[4:5], vcc
	s_xor_b64 s[4:5], exec, s[4:5]
	v_add_u32_e32 v2, 0xfffffef0, v2
	v_mul_hi_u32 v3, v2, s96
	v_lshrrev_b32_e32 v3, 3, v3
	v_add_u32_e32 v4, 16, v3
	v_lshl_add_u32 v3, v3, 5, v3
	v_sub_u32_e32 v7, v2, v3
	s_or_saveexec_b64 s[22:23], s[4:5]
	v_mov_b32_e32 v6, 0x1000
	s_xor_b64 exec, exec, s[22:23]
	v_mul_hi_i32 v3, v2, s97
	v_lshrrev_b32_e32 v4, 31, v3
	v_ashrrev_i32_e32 v3, 3, v3
	v_add_u32_e32 v4, v3, v4
	v_lshl_add_u32 v3, v4, 4, v4
	v_sub_u32_e32 v7, v2, v3
	v_mov_b32_e32 v6, 0x800
	s_or_b64 exec, exec, s[22:23]
	v_cmp_lt_i32_e32 vcc, 15, v4
	s_and_saveexec_b64 s[4:5], vcc
	s_xor_b64 s[4:5], exec, s[4:5]
	v_add_u32_e32 v2, -16, v4
	v_mov_b32_e32 v3, v0
	v_lshlrev_b64 v[2:3], 12, v[2:3]
	v_lshl_add_u64 v[2:3], v[2:3], 0, s[42:43]
	s_andn2_saveexec_b64 s[4:5], s[4:5]
	v_ashrrev_i32_e32 v5, 31, v4
	v_lshlrev_b64 v[2:3], 11, v[4:5]
	s_or_b64 exec, exec, s[4:5]
	v_and_b32_e32 v5, 0x7f, v1
	v_cmp_gt_i32_e32 vcc, s79, v5
	s_and_saveexec_b64 s[22:23], vcc
	s_cbranch_execz .LBB0_356
	v_cmp_ne_u32_e32 vcc, 0, v5
	s_and_b64 exec, exec, vcc
	s_cbranch_execz .LBB0_356
	v_mul_lo_u32 v7, v7, s54
	v_add3_u32 v4, v5, v7, -1
	v_cmp_lt_i32_e32 vcc, v4, v6
	s_and_b64 exec, exec, vcc
	s_cbranch_execz .LBB0_356
	v_cmp_lt_i32_e32 vcc, 0, v4
	v_mov_b32_e32 v19, 0
	v_mov_b32_e32 v18, 0
	s_and_saveexec_b64 s[4:5], vcc
	v_mov_b32_e32 v8, 0x11ffc
	v_lshl_add_u32 v8, v1, 2, v8
	ds_read_b32 v18, v8
	s_or_b64 exec, exec, s[4:5]
	v_add_u32_e32 v5, v7, v5
	v_cmp_lt_i32_e32 vcc, v5, v6
	v_lshl_add_u32 v5, v1, 2, v175
	ds_read_b32 v20, v5
	s_and_saveexec_b64 s[4:5], vcc
	ds_read_b32 v19, v5 offset:4
	s_or_b64 exec, exec, s[4:5]
	s_lshl_b32 s4, s20, 6
	s_ashr_i32 s5, s4, 31
	s_lshl_b64 s[4:5], s[4:5], 1
	s_add_u32 s4, s30, s4
	v_ashrrev_i32_e32 v5, 31, v4
	s_addc_u32 s5, s31, s5
	v_lshl_add_u64 v[2:3], v[2:3], 0, v[4:5]
	v_mov_b64_e32 v[4:5], s[4:5]
	v_mad_u64_u32 v[22:23], s[4:5], v2, s3, v[4:5]
	v_mov_b32_e32 v2, v23
	v_mul_lo_u32 v1, v1, s33
	v_mad_u64_u32 v[2:3], s[4:5], v3, s3, v[2:3]
	v_add_u32_e32 v1, 0xfffffef0, v1
	v_mov_b32_e32 v23, v2
	s_mov_b32 s4, 0
	s_mov_b32 s5, 0
	v_add_u32_e32 v251, 0x190, v1
.LBB0_452:
	s_add_i32 s21, s5, 0x124c0
	v_add_u32_e32 v48, s5, v1
	v_mov_b32_e32 v21, s21
	s_add_i32 s21, s5, 0x125c0
	ds_read_b128 v[6:9], v48
	ds_read_b128 v[2:5], v48 offset:16
	ds_read_b128 v[10:13], v48 offset:272
	ds_read_b128 v[14:17], v48 offset:544
	ds_read_b128 v[24:27], v48 offset:400
	ds_read_b128 v[28:31], v21
	v_mov_b32_e32 v21, s21
	s_add_i32 s21, s5, 0x126c0
	ds_read_b128 v[32:35], v21
	v_mov_b32_e32 v21, s21
	ds_read_b128 v[36:39], v21
	s_add_i32 s21, s5, 0x127c0
	v_mov_b32_e32 v21, s21
	ds_read_b128 v[40:43], v21
	s_waitcnt lgkmcnt(0)
	v_mov_b32_e32 v44, v6
	v_mov_b32_e32 v45, v14
	v_pk_mul_f32 v[44:45], v[18:19], v[44:45]
	v_mov_b32_e32 v46, v28
	v_mov_b32_e32 v47, v36
	v_mul_f32_e32 v10, v20, v10
	v_pk_mul_f32 v[44:45], v[44:45], v[46:47]
	v_mov_b32_e32 v14, v7
	v_fma_f32 v6, v10, v32, v44
	v_add_f32_e32 v6, v6, v45
	v_add_f32_e32 v21, v6, v40
	v_mul_f32_e32 v6, 0xbfb8aa3b, v21
	v_exp_f32_e32 v6, v6
	v_mov_b32_e32 v36, v29
	v_mul_f32_e32 v10, v20, v11
	v_mov_b32_e32 v44, v24
	v_add_f32_e32 v6, 1.0, v6
	v_rcp_f32_e32 v45, v6
	v_pk_mul_f32 v[6:7], v[18:19], v[14:15]
	v_mov_b32_e32 v11, v38
	v_pk_mul_f32 v[6:7], v[6:7], v[36:37]
	v_pk_mul_f32 v[44:45], v[20:21], v[44:45]
	v_fma_f32 v6, v10, v33, v6
	v_add_f32_e32 v6, v6, v7
	v_add_f32_e32 v21, v6, v41
	v_mul_f32_e32 v6, 0xbfb8aa3b, v21
	v_exp_f32_e32 v6, v6
	v_mul_f32_e32 v44, v44, v45
	v_mov_b32_e32 v10, v30
	v_mul_f32_e32 v12, v20, v12
	v_add_f32_e32 v6, 1.0, v6
	v_rcp_f32_e32 v7, v6
	v_mov_b32_e32 v6, v25
	v_mov_b32_e32 v38, v31
	s_lshl_b32 s21, s4, 2
	v_pk_mul_f32 v[6:7], v[20:21], v[6:7]
	s_or_b32 s21, s21, 0x90
	v_mul_f32_e32 v45, v6, v7
	v_mov_b32_e32 v6, v8
	v_mov_b32_e32 v7, v16
	v_pk_mul_f32 v[6:7], v[18:19], v[6:7]
	v_mov_b32_e32 v16, v9
	v_pk_mul_f32 v[6:7], v[6:7], v[10:11]
	v_mul_f32_e32 v8, v20, v13
	v_fma_f32 v6, v12, v34, v6
	v_add_f32_e32 v6, v6, v7
	v_add_f32_e32 v21, v6, v42
	v_mul_f32_e32 v6, 0xbfb8aa3b, v21
	v_exp_f32_e32 v6, v6
	s_add_i32 s24, s21, 0x12440
	v_mov_b32_e32 v40, v2
	s_add_i32 s5, s5, 32
	v_add_f32_e32 v6, 1.0, v6
	v_rcp_f32_e32 v7, v6
	v_mov_b32_e32 v6, v26
	s_add_i32 s4, s4, 8
	v_pk_mul_f32 v[6:7], v[20:21], v[6:7]
	s_nop 0
	v_mul_f32_e32 v46, v6, v7
	v_pk_mul_f32 v[6:7], v[18:19], v[16:17]
	s_nop 0
	v_pk_mul_f32 v[6:7], v[6:7], v[38:39]
	s_nop 0
	v_fma_f32 v6, v8, v35, v6
	v_add_f32_e32 v6, v6, v7
	v_add_f32_e32 v21, v6, v43
	v_mul_f32_e32 v6, 0xbfb8aa3b, v21
	v_exp_f32_e32 v6, v6
	s_nop 0
	v_add_f32_e32 v6, 1.0, v6
	v_rcp_f32_e32 v7, v6
	v_mov_b32_e32 v6, v27
	v_pk_mul_f32 v[6:7], v[20:21], v[6:7]
	v_mov_b32_e32 v21, s24
	s_add_i32 s24, s21, 0x12540
	v_mul_f32_e32 v47, v6, v7
	ds_read_b128 v[14:17], v48 offset:288
	ds_read_b128 v[10:13], v48 offset:560
	ds_read_b128 v[6:9], v48 offset:416
	ds_read_b128 v[24:27], v21
	v_mov_b32_e32 v21, s24
	s_add_i32 s24, s21, 0x12640
	ds_read_b128 v[28:31], v21
	v_mov_b32_e32 v21, s24
	ds_read_b128 v[32:35], v21
	s_add_i32 s21, s21, 0x12740
	v_mov_b32_e32 v21, s21
	ds_read_b128 v[36:39], v21
	s_waitcnt lgkmcnt(0)
	v_mov_b32_e32 v41, v10
	v_pk_mul_f32 v[40:41], v[18:19], v[40:41]
	v_mov_b32_e32 v42, v24
	v_mov_b32_e32 v43, v32
	v_mul_f32_e32 v14, v20, v14
	v_pk_mul_f32 v[40:41], v[40:41], v[42:43]
	v_mov_b32_e32 v10, v3
	v_fma_f32 v2, v14, v28, v40
	v_add_f32_e32 v2, v2, v41
	v_add_f32_e32 v21, v2, v36
	v_mul_f32_e32 v2, 0xbfb8aa3b, v21
	v_exp_f32_e32 v2, v2
	v_mov_b32_e32 v32, v25
	v_mov_b32_e32 v40, v6
	v_mul_f32_e32 v6, v20, v15
	v_add_f32_e32 v2, 1.0, v2
	v_rcp_f32_e32 v41, v2
	v_pk_mul_f32 v[2:3], v[18:19], v[10:11]
	v_mul_f32_e32 v11, v20, v16
	v_pk_mul_f32 v[2:3], v[2:3], v[32:33]
	v_pk_mul_f32 v[40:41], v[20:21], v[40:41]
	v_fma_f32 v2, v6, v29, v2
	v_add_f32_e32 v2, v2, v3
	v_add_f32_e32 v21, v2, v37
	v_mul_f32_e32 v2, 0xbfb8aa3b, v21
	v_exp_f32_e32 v2, v2
	v_mov_b32_e32 v6, v26
	v_mul_f32_e32 v14, v40, v41
	s_cmpk_lg_i32 s5, 0x80
	v_add_f32_e32 v2, 1.0, v2
	v_rcp_f32_e32 v3, v2
	v_mov_b32_e32 v2, v7
	v_mov_b32_e32 v7, v34
	v_mov_b32_e32 v34, v27
	v_pk_mul_f32 v[2:3], v[20:21], v[2:3]
	s_nop 0
	v_mul_f32_e32 v10, v2, v3
	v_mov_b32_e32 v2, v4
	v_mov_b32_e32 v3, v12
	v_pk_mul_f32 v[2:3], v[18:19], v[2:3]
	v_mov_b32_e32 v12, v5
	v_pk_mul_f32 v[2:3], v[2:3], v[6:7]
	v_mul_f32_e32 v4, v20, v17
	v_fma_f32 v2, v11, v30, v2
	v_add_f32_e32 v2, v2, v3
	v_add_f32_e32 v21, v2, v38
	v_mul_f32_e32 v2, 0xbfb8aa3b, v21
	v_exp_f32_e32 v2, v2
	s_nop 0
	v_add_f32_e32 v2, 1.0, v2
	v_rcp_f32_e32 v3, v2
	v_mov_b32_e32 v2, v8
	v_pk_mul_f32 v[2:3], v[20:21], v[2:3]
	s_nop 0
	v_mul_f32_e32 v6, v2, v3
	v_pk_mul_f32 v[2:3], v[18:19], v[12:13]
	s_nop 0
	v_pk_mul_f32 v[2:3], v[2:3], v[34:35]
	s_nop 0
	v_fma_f32 v2, v4, v31, v2
	v_add_f32_e32 v2, v2, v3
	v_add_f32_e32 v21, v2, v39
	v_mul_f32_e32 v2, 0xbfb8aa3b, v21
	v_exp_f32_e32 v2, v2
	v_cvt_pk_bf16_f32 v4, v14, v10
	s_nop 0
	v_add_f32_e32 v2, 1.0, v2
	v_rcp_f32_e32 v3, v2
	v_mov_b32_e32 v2, v9
	v_pk_mul_f32 v[2:3], v[20:21], v[2:3]
	s_nop 0
	v_mul_f32_e32 v5, v2, v3
	v_cvt_pk_bf16_f32 v2, v44, v45
	v_cvt_pk_bf16_f32 v3, v46, v47
	v_cvt_pk_bf16_f32 v5, v6, v5
	ds_write_b128 v251, v[2:5]
	v_lshl_add_u64 v[22:23], v[22:23], 0, 16
	v_add_u32_e32 v251, 16, v251
	s_cbranch_scc1 .LBB0_452
	s_mov_b64 vcc, exec
	s_cmp_eq_u64 vcc, 0
	s_cbranch_scc1 .Lup_skip_p1
	v_readfirstlane_b32 s4, v22
	v_readfirstlane_b32 s5, v23
	s_ff1_i32_b64 s32, vcc
	s_or_b64 exec, exec, s[22:23]
	v_and_b32_e32 v242, 63, v170
	v_lshrrev_b32_e32 v243, 2, v242
	v_and_b32_e32 v244, 3, v242
	v_lshlrev_b32_e32 v244, 4, v244
	v_sub_u32_e32 v245, v170, v242
	v_add_u32_e32 v245, s32, v245
	v_mul_u32_u24_e32 v245, 0x110, v245
	v_add_u32_e32 v245, v245, v244
	v_add_u32_e32 v245, 0x80, v245
	s_waitcnt lgkmcnt(0)
	v_add_u32_e32 v246, 0, v243
	v_lshrrev_b64 v[236:237], v246, vcc
	v_and_b32_e32 v236, 1, v236
	v_subrev_u32_e32 v246, s32, v246
	v_mul_i32_i24_e32 v246, v246, v236
	v_mul_i32_i24_e32 v238, 0x110, v246
	v_add_u32_e32 v238, v238, v245
	ds_read_b128 v[232:235], v238
	v_mul_i32_i24_e32 v238, 0x1580, v246
	v_add_u32_e32 v238, v238, v244
	v_add_u32_e32 v238, 0xffffffc0, v238
	v_ashrrev_i32_e32 v239, 31, v238
	v_lshl_add_u64 v[240:241], v[238:239], 0, s[4:5]
	s_waitcnt lgkmcnt(0)
	global_store_dwordx4 v[240:241], v[232:235], off
	s_nop 1
	v_add_u32_e32 v246, 16, v243
	v_lshrrev_b64 v[236:237], v246, vcc
	v_and_b32_e32 v236, 1, v236
	v_subrev_u32_e32 v246, s32, v246
	v_mul_i32_i24_e32 v246, v246, v236
	v_mul_i32_i24_e32 v238, 0x110, v246
	v_add_u32_e32 v238, v238, v245
	ds_read_b128 v[232:235], v238
	v_mul_i32_i24_e32 v238, 0x1580, v246
	v_add_u32_e32 v238, v238, v244
	v_add_u32_e32 v238, 0xffffffc0, v238
	v_ashrrev_i32_e32 v239, 31, v238
	v_lshl_add_u64 v[240:241], v[238:239], 0, s[4:5]
	s_waitcnt lgkmcnt(0)
	global_store_dwordx4 v[240:241], v[232:235], off
	s_nop 1
	v_add_u32_e32 v246, 32, v243
	v_lshrrev_b64 v[236:237], v246, vcc
	v_and_b32_e32 v236, 1, v236
	v_subrev_u32_e32 v246, s32, v246
	v_mul_i32_i24_e32 v246, v246, v236
	v_mul_i32_i24_e32 v238, 0x110, v246
	v_add_u32_e32 v238, v238, v245
	ds_read_b128 v[232:235], v238
	v_mul_i32_i24_e32 v238, 0x1580, v246
	v_add_u32_e32 v238, v238, v244
	v_add_u32_e32 v238, 0xffffffc0, v238
	v_ashrrev_i32_e32 v239, 31, v238
	v_lshl_add_u64 v[240:241], v[238:239], 0, s[4:5]
	s_waitcnt lgkmcnt(0)
	global_store_dwordx4 v[240:241], v[232:235], off
	s_nop 1
	v_add_u32_e32 v246, 48, v243
	v_lshrrev_b64 v[236:237], v246, vcc
	v_and_b32_e32 v236, 1, v236
	v_subrev_u32_e32 v246, s32, v246
	v_mul_i32_i24_e32 v246, v246, v236
	v_mul_i32_i24_e32 v238, 0x110, v246
	v_add_u32_e32 v238, v238, v245
	ds_read_b128 v[232:235], v238
	v_mul_i32_i24_e32 v238, 0x1580, v246
	v_add_u32_e32 v238, v238, v244
	v_add_u32_e32 v238, 0xffffffc0, v238
	v_ashrrev_i32_e32 v239, 31, v238
	v_lshl_add_u64 v[240:241], v[238:239], 0, s[4:5]
	s_waitcnt lgkmcnt(0)
	global_store_dwordx4 v[240:241], v[232:235], off
	s_nop 1
.Lup_skip_p1:
	s_branch .LBB0_356
